# S5 pass2: LDS staging replaced by v_permlane32_swap transposition; out-proj ssq row reduction via DPP instead of ds_bpermute
# speedup vs baseline: 1.0064x; 1.0064x over previous
.LBB0_466:
	v_cndmask_b32_e64 v101, 0, 1, s[40:41]
	v_cmp_ne_u32_e64 s[12:13], 1, v101
	s_andn2_b64 vcc, exec, s[40:41]
	s_cbranch_vccnz .LBB0_470
	v_mul_f32_e32 v93, v93, v93
	v_fmac_f32_e32 v93, v92, v92
	v_mul_f32_e32 v92, v95, v95
	v_fmac_f32_e32 v92, v94, v94
	v_add_f32_e32 v92, v93, v92
	s_nop 1
	v_add_f32_dpp v92, v92, v92 quad_perm:[1,0,3,2] row_mask:0xf bank_mask:0xf
	s_nop 1
	v_add_f32_dpp v92, v92, v92 quad_perm:[2,3,0,1] row_mask:0xf bank_mask:0xf
	s_nop 1
	v_add_f32_dpp v92, v92, v92 row_half_mirror row_mask:0xf bank_mask:0xf
	s_nop 1
	v_add_f32_dpp v92, v92, v92 row_mirror row_mask:0xf bank_mask:0xf
	v_mov_b32_e32 v93, v92
	s_nop 1
	v_permlane16_swap_b32_e32 v92, v93
	v_add_f32_e32 v92, v92, v93
	v_mov_b32_e32 v93, v92
	s_nop 1
	v_permlane32_swap_b32_e32 v92, v93
	s_and_saveexec_b64 s[46:47], s[4:5]
	s_cbranch_execz .LBB0_469
	s_add_i32 s52, s28, s24
	s_ashr_i32 s53, s52, 31
	s_lshl_b64 s[52:53], s[52:53], 5
	s_add_u32 s52, s50, s52
	s_addc_u32 s53, s51, s53
	v_add_f32_e32 v92, v92, v93
	global_store_dword v209, v92, s[52:53]

.LBB0_474:
	s_and_b64 vcc, exec, s[12:13]
	s_cbranch_vccnz .LBB0_478
	v_mul_f32_e32 v89, v89, v89
	v_fmac_f32_e32 v89, v88, v88
	v_mul_f32_e32 v88, v91, v91
	v_fmac_f32_e32 v88, v90, v90
	v_add_f32_e32 v88, v89, v88
	s_nop 1
	v_add_f32_dpp v88, v88, v88 quad_perm:[1,0,3,2] row_mask:0xf bank_mask:0xf
	s_nop 1
	v_add_f32_dpp v88, v88, v88 quad_perm:[2,3,0,1] row_mask:0xf bank_mask:0xf
	s_nop 1
	v_add_f32_dpp v88, v88, v88 row_half_mirror row_mask:0xf bank_mask:0xf
	s_nop 1
	v_add_f32_dpp v88, v88, v88 row_mirror row_mask:0xf bank_mask:0xf
	v_mov_b32_e32 v89, v88
	s_nop 1
	v_permlane16_swap_b32_e32 v88, v89
	v_add_f32_e32 v88, v88, v89
	v_mov_b32_e32 v89, v88
	s_nop 1
	v_permlane32_swap_b32_e32 v88, v89
	s_and_saveexec_b64 s[46:47], s[4:5]
	s_cbranch_execz .LBB0_477
	s_add_i32 s52, s28, s25
	s_ashr_i32 s53, s52, 31
	s_lshl_b64 s[52:53], s[52:53], 5
	s_add_u32 s52, s50, s52
	s_addc_u32 s53, s51, s53
	v_add_f32_e32 v88, v88, v89
	global_store_dword v209, v88, s[52:53]

.LBB0_482:
	s_and_b64 vcc, exec, s[12:13]
	s_cbranch_vccnz .LBB0_486
	v_mul_f32_e32 v85, v85, v85
	v_fmac_f32_e32 v85, v84, v84
	v_mul_f32_e32 v84, v87, v87
	v_fmac_f32_e32 v84, v86, v86
	v_add_f32_e32 v84, v85, v84
	s_nop 1
	v_add_f32_dpp v84, v84, v84 quad_perm:[1,0,3,2] row_mask:0xf bank_mask:0xf
	s_nop 1
	v_add_f32_dpp v84, v84, v84 quad_perm:[2,3,0,1] row_mask:0xf bank_mask:0xf
	s_nop 1
	v_add_f32_dpp v84, v84, v84 row_half_mirror row_mask:0xf bank_mask:0xf
	s_nop 1
	v_add_f32_dpp v84, v84, v84 row_mirror row_mask:0xf bank_mask:0xf
	v_mov_b32_e32 v85, v84
	s_nop 1
	v_permlane16_swap_b32_e32 v84, v85
	v_add_f32_e32 v84, v84, v85
	v_mov_b32_e32 v85, v84
	s_nop 1
	v_permlane32_swap_b32_e32 v84, v85
	s_and_saveexec_b64 s[46:47], s[4:5]
	s_cbranch_execz .LBB0_485
	s_add_i32 s52, s28, s30
	s_ashr_i32 s53, s52, 31
	s_lshl_b64 s[52:53], s[52:53], 5
	s_add_u32 s52, s50, s52
	s_addc_u32 s53, s51, s53
	v_add_f32_e32 v84, v84, v85
	global_store_dword v209, v84, s[52:53]

.LBB0_490:
	s_and_b64 vcc, exec, s[12:13]
	s_cbranch_vccnz .LBB0_494
	v_mul_f32_e32 v81, v81, v81
	v_fmac_f32_e32 v81, v80, v80
	v_mul_f32_e32 v80, v83, v83
	v_fmac_f32_e32 v80, v82, v82
	v_add_f32_e32 v80, v81, v80
	s_nop 1
	v_add_f32_dpp v80, v80, v80 quad_perm:[1,0,3,2] row_mask:0xf bank_mask:0xf
	s_nop 1
	v_add_f32_dpp v80, v80, v80 quad_perm:[2,3,0,1] row_mask:0xf bank_mask:0xf
	s_nop 1
	v_add_f32_dpp v80, v80, v80 row_half_mirror row_mask:0xf bank_mask:0xf
	s_nop 1
	v_add_f32_dpp v80, v80, v80 row_mirror row_mask:0xf bank_mask:0xf
	v_mov_b32_e32 v81, v80
	s_nop 1
	v_permlane16_swap_b32_e32 v80, v81
	v_add_f32_e32 v80, v80, v81
	v_mov_b32_e32 v81, v80
	s_nop 1
	v_permlane32_swap_b32_e32 v80, v81
	s_and_saveexec_b64 s[46:47], s[4:5]
	s_cbranch_execz .LBB0_493
	s_add_i32 s52, s28, s33
	s_ashr_i32 s53, s52, 31
	s_lshl_b64 s[52:53], s[52:53], 5
	s_add_u32 s52, s50, s52
	s_addc_u32 s53, s51, s53
	v_add_f32_e32 v80, v80, v81
	global_store_dword v209, v80, s[52:53]

.LBB0_498:
	s_and_b64 vcc, exec, s[12:13]
	s_cbranch_vccnz .LBB0_502
	v_mul_f32_e32 v77, v77, v77
	v_fmac_f32_e32 v77, v76, v76
	v_mul_f32_e32 v76, v79, v79
	v_fmac_f32_e32 v76, v78, v78
	v_add_f32_e32 v76, v77, v76
	s_nop 1
	v_add_f32_dpp v76, v76, v76 quad_perm:[1,0,3,2] row_mask:0xf bank_mask:0xf
	s_nop 1
	v_add_f32_dpp v76, v76, v76 quad_perm:[2,3,0,1] row_mask:0xf bank_mask:0xf
	s_nop 1
	v_add_f32_dpp v76, v76, v76 row_half_mirror row_mask:0xf bank_mask:0xf
	s_nop 1
	v_add_f32_dpp v76, v76, v76 row_mirror row_mask:0xf bank_mask:0xf
	v_mov_b32_e32 v77, v76
	s_nop 1
	v_permlane16_swap_b32_e32 v76, v77
	v_add_f32_e32 v76, v76, v77
	v_mov_b32_e32 v77, v76
	s_nop 1
	v_permlane32_swap_b32_e32 v76, v77
	s_and_saveexec_b64 s[46:47], s[4:5]
	s_cbranch_execz .LBB0_501
	s_add_i32 s52, s28, s36
	s_ashr_i32 s53, s52, 31
	s_lshl_b64 s[52:53], s[52:53], 5
	s_add_u32 s52, s50, s52
	s_addc_u32 s53, s51, s53
	v_add_f32_e32 v76, v76, v77
	global_store_dword v209, v76, s[52:53]

.LBB0_506:
	s_and_b64 vcc, exec, s[12:13]
	s_cbranch_vccnz .LBB0_510
	v_mul_f32_e32 v73, v73, v73
	v_fmac_f32_e32 v73, v72, v72
	v_mul_f32_e32 v72, v75, v75
	v_fmac_f32_e32 v72, v74, v74
	v_add_f32_e32 v72, v73, v72
	s_nop 1
	v_add_f32_dpp v72, v72, v72 quad_perm:[1,0,3,2] row_mask:0xf bank_mask:0xf
	s_nop 1
	v_add_f32_dpp v72, v72, v72 quad_perm:[2,3,0,1] row_mask:0xf bank_mask:0xf
	s_nop 1
	v_add_f32_dpp v72, v72, v72 row_half_mirror row_mask:0xf bank_mask:0xf
	s_nop 1
	v_add_f32_dpp v72, v72, v72 row_mirror row_mask:0xf bank_mask:0xf
	v_mov_b32_e32 v73, v72
	s_nop 1
	v_permlane16_swap_b32_e32 v72, v73
	v_add_f32_e32 v72, v72, v73
	v_mov_b32_e32 v73, v72
	s_nop 1
	v_permlane32_swap_b32_e32 v72, v73
	s_and_saveexec_b64 s[46:47], s[4:5]
	s_cbranch_execz .LBB0_509
	s_add_i32 s52, s28, s37
	s_ashr_i32 s53, s52, 31
	s_lshl_b64 s[52:53], s[52:53], 5
	s_add_u32 s52, s50, s52
	s_addc_u32 s53, s51, s53
	v_add_f32_e32 v72, v72, v73
	global_store_dword v209, v72, s[52:53]

.LBB0_514:
	s_and_b64 vcc, exec, s[12:13]
	s_cbranch_vccnz .LBB0_518
	v_mul_f32_e32 v69, v69, v69
	v_fmac_f32_e32 v69, v68, v68
	v_mul_f32_e32 v68, v71, v71
	v_fmac_f32_e32 v68, v70, v70
	v_add_f32_e32 v68, v69, v68
	s_nop 1
	v_add_f32_dpp v68, v68, v68 quad_perm:[1,0,3,2] row_mask:0xf bank_mask:0xf
	s_nop 1
	v_add_f32_dpp v68, v68, v68 quad_perm:[2,3,0,1] row_mask:0xf bank_mask:0xf
	s_nop 1
	v_add_f32_dpp v68, v68, v68 row_half_mirror row_mask:0xf bank_mask:0xf
	s_nop 1
	v_add_f32_dpp v68, v68, v68 row_mirror row_mask:0xf bank_mask:0xf
	v_mov_b32_e32 v69, v68
	s_nop 1
	v_permlane16_swap_b32_e32 v68, v69
	v_add_f32_e32 v68, v68, v69
	v_mov_b32_e32 v69, v68
	s_nop 1
	v_permlane32_swap_b32_e32 v68, v69
	s_and_saveexec_b64 s[46:47], s[4:5]
	s_cbranch_execz .LBB0_517
	s_add_i32 s52, s28, s48
	s_ashr_i32 s53, s52, 31
	s_lshl_b64 s[52:53], s[52:53], 5
	s_add_u32 s52, s50, s52
	s_addc_u32 s53, s51, s53
	v_add_f32_e32 v68, v68, v69
	global_store_dword v209, v68, s[52:53]

.LBB0_522:
	s_and_b64 vcc, exec, s[12:13]
	s_cbranch_vccnz .LBB0_410
	v_mul_f32_e32 v65, v65, v65
	v_fmac_f32_e32 v65, v64, v64
	v_mul_f32_e32 v64, v67, v67
	v_fmac_f32_e32 v64, v66, v66
	v_add_f32_e32 v64, v65, v64
	s_nop 1
	v_add_f32_dpp v64, v64, v64 quad_perm:[1,0,3,2] row_mask:0xf bank_mask:0xf
	s_nop 1
	v_add_f32_dpp v64, v64, v64 quad_perm:[2,3,0,1] row_mask:0xf bank_mask:0xf
	s_nop 1
	v_add_f32_dpp v64, v64, v64 row_half_mirror row_mask:0xf bank_mask:0xf
	s_nop 1
	v_add_f32_dpp v64, v64, v64 row_mirror row_mask:0xf bank_mask:0xf
	v_mov_b32_e32 v65, v64
	s_nop 1
	v_permlane16_swap_b32_e32 v64, v65
	v_add_f32_e32 v64, v64, v65
	v_mov_b32_e32 v65, v64
	s_nop 1
	v_permlane32_swap_b32_e32 v64, v65
	s_and_saveexec_b64 s[10:11], s[4:5]
	s_cbranch_execz .LBB0_409
	s_add_i32 s12, s28, s49
	s_ashr_i32 s13, s12, 31
	s_lshl_b64 s[12:13], s[12:13], 5
	s_add_u32 s12, s50, s12
	s_addc_u32 s13, s51, s13
	v_add_f32_e32 v64, v64, v65
	global_store_dword v209, v64, s[12:13]
	s_branch .LBB0_409

.LBB0_583:
	v_cndmask_b32_e64 v37, 0, 1, s[40:41]
	s_add_i32 s28, s28, s44
	v_cmp_ne_u32_e64 s[12:13], 1, v37
	s_andn2_b64 vcc, exec, s[40:41]
	s_cbranch_vccnz .LBB0_587
	v_mul_f32_e32 v29, v29, v29
	v_fmac_f32_e32 v29, v28, v28
	v_mul_f32_e32 v28, v31, v31
	v_fmac_f32_e32 v28, v30, v30
	v_add_f32_e32 v28, v29, v28
	s_nop 1
	v_add_f32_dpp v28, v28, v28 quad_perm:[1,0,3,2] row_mask:0xf bank_mask:0xf
	s_nop 1
	v_add_f32_dpp v28, v28, v28 quad_perm:[2,3,0,1] row_mask:0xf bank_mask:0xf
	s_nop 1
	v_add_f32_dpp v28, v28, v28 row_half_mirror row_mask:0xf bank_mask:0xf
	s_nop 1
	v_add_f32_dpp v28, v28, v28 row_mirror row_mask:0xf bank_mask:0xf
	v_mov_b32_e32 v29, v28
	s_nop 1
	v_permlane16_swap_b32_e32 v28, v29
	v_add_f32_e32 v28, v28, v29
	v_mov_b32_e32 v29, v28
	s_nop 1
	v_permlane32_swap_b32_e32 v28, v29
	s_and_saveexec_b64 s[42:43], s[4:5]
	s_cbranch_execz .LBB0_586
	s_add_i32 s46, s28, s24
	s_ashr_i32 s47, s46, 31
	s_lshl_b64 s[46:47], s[46:47], 5
	s_add_u32 s46, s50, s46
	s_addc_u32 s47, s51, s47
	v_add_f32_e32 v28, v28, v29
	global_store_dword v209, v28, s[46:47]

.LBB0_591:
	s_and_b64 vcc, exec, s[12:13]
	s_cbranch_vccnz .LBB0_595
	v_mul_f32_e32 v25, v25, v25
	v_fmac_f32_e32 v25, v24, v24
	v_mul_f32_e32 v24, v27, v27
	v_fmac_f32_e32 v24, v26, v26
	v_add_f32_e32 v24, v25, v24
	s_nop 1
	v_add_f32_dpp v24, v24, v24 quad_perm:[1,0,3,2] row_mask:0xf bank_mask:0xf
	s_nop 1
	v_add_f32_dpp v24, v24, v24 quad_perm:[2,3,0,1] row_mask:0xf bank_mask:0xf
	s_nop 1
	v_add_f32_dpp v24, v24, v24 row_half_mirror row_mask:0xf bank_mask:0xf
	s_nop 1
	v_add_f32_dpp v24, v24, v24 row_mirror row_mask:0xf bank_mask:0xf
	v_mov_b32_e32 v25, v24
	s_nop 1
	v_permlane16_swap_b32_e32 v24, v25
	v_add_f32_e32 v24, v24, v25
	v_mov_b32_e32 v25, v24
	s_nop 1
	v_permlane32_swap_b32_e32 v24, v25
	s_and_saveexec_b64 s[42:43], s[4:5]
	s_cbranch_execz .LBB0_594
	s_add_i32 s46, s28, s25
	s_ashr_i32 s47, s46, 31
	s_lshl_b64 s[46:47], s[46:47], 5
	s_add_u32 s46, s50, s46
	s_addc_u32 s47, s51, s47
	v_add_f32_e32 v24, v24, v25
	global_store_dword v209, v24, s[46:47]

.LBB0_599:
	s_and_b64 vcc, exec, s[12:13]
	s_cbranch_vccnz .LBB0_603
	v_mul_f32_e32 v21, v21, v21
	v_fmac_f32_e32 v21, v20, v20
	v_mul_f32_e32 v20, v23, v23
	v_fmac_f32_e32 v20, v22, v22
	v_add_f32_e32 v20, v21, v20
	s_nop 1
	v_add_f32_dpp v20, v20, v20 quad_perm:[1,0,3,2] row_mask:0xf bank_mask:0xf
	s_nop 1
	v_add_f32_dpp v20, v20, v20 quad_perm:[2,3,0,1] row_mask:0xf bank_mask:0xf
	s_nop 1
	v_add_f32_dpp v20, v20, v20 row_half_mirror row_mask:0xf bank_mask:0xf
	s_nop 1
	v_add_f32_dpp v20, v20, v20 row_mirror row_mask:0xf bank_mask:0xf
	v_mov_b32_e32 v21, v20
	s_nop 1
	v_permlane16_swap_b32_e32 v20, v21
	v_add_f32_e32 v20, v20, v21
	v_mov_b32_e32 v21, v20
	s_nop 1
	v_permlane32_swap_b32_e32 v20, v21
	s_and_saveexec_b64 s[42:43], s[4:5]
	s_cbranch_execz .LBB0_602
	s_add_i32 s46, s28, s30
	s_ashr_i32 s47, s46, 31
	s_lshl_b64 s[46:47], s[46:47], 5
	s_add_u32 s46, s50, s46
	s_addc_u32 s47, s51, s47
	v_add_f32_e32 v20, v20, v21
	global_store_dword v209, v20, s[46:47]

.LBB0_607:
	s_and_b64 vcc, exec, s[12:13]
	s_cbranch_vccnz .LBB0_611
	v_mul_f32_e32 v17, v17, v17
	v_fmac_f32_e32 v17, v16, v16
	v_mul_f32_e32 v16, v19, v19
	v_fmac_f32_e32 v16, v18, v18
	v_add_f32_e32 v16, v17, v16
	s_nop 1
	v_add_f32_dpp v16, v16, v16 quad_perm:[1,0,3,2] row_mask:0xf bank_mask:0xf
	s_nop 1
	v_add_f32_dpp v16, v16, v16 quad_perm:[2,3,0,1] row_mask:0xf bank_mask:0xf
	s_nop 1
	v_add_f32_dpp v16, v16, v16 row_half_mirror row_mask:0xf bank_mask:0xf
	s_nop 1
	v_add_f32_dpp v16, v16, v16 row_mirror row_mask:0xf bank_mask:0xf
	v_mov_b32_e32 v17, v16
	s_nop 1
	v_permlane16_swap_b32_e32 v16, v17
	v_add_f32_e32 v16, v16, v17
	v_mov_b32_e32 v17, v16
	s_nop 1
	v_permlane32_swap_b32_e32 v16, v17
	s_and_saveexec_b64 s[42:43], s[4:5]
	s_cbranch_execz .LBB0_610
	s_add_i32 s46, s28, s33
	s_ashr_i32 s47, s46, 31
	s_lshl_b64 s[46:47], s[46:47], 5
	s_add_u32 s46, s50, s46
	s_addc_u32 s47, s51, s47
	v_add_f32_e32 v16, v16, v17
	global_store_dword v209, v16, s[46:47]

.LBB0_615:
	s_and_b64 vcc, exec, s[12:13]
	s_cbranch_vccnz .LBB0_619
	v_mul_f32_e32 v13, v13, v13
	v_fmac_f32_e32 v13, v12, v12
	v_mul_f32_e32 v12, v15, v15
	v_fmac_f32_e32 v12, v14, v14
	v_add_f32_e32 v12, v13, v12
	s_nop 1
	v_add_f32_dpp v12, v12, v12 quad_perm:[1,0,3,2] row_mask:0xf bank_mask:0xf
	s_nop 1
	v_add_f32_dpp v12, v12, v12 quad_perm:[2,3,0,1] row_mask:0xf bank_mask:0xf
	s_nop 1
	v_add_f32_dpp v12, v12, v12 row_half_mirror row_mask:0xf bank_mask:0xf
	s_nop 1
	v_add_f32_dpp v12, v12, v12 row_mirror row_mask:0xf bank_mask:0xf
	v_mov_b32_e32 v13, v12
	s_nop 1
	v_permlane16_swap_b32_e32 v12, v13
	v_add_f32_e32 v12, v12, v13
	v_mov_b32_e32 v13, v12
	s_nop 1
	v_permlane32_swap_b32_e32 v12, v13
	s_and_saveexec_b64 s[42:43], s[4:5]
	s_cbranch_execz .LBB0_618
	s_add_i32 s46, s28, s36
	s_ashr_i32 s47, s46, 31
	s_lshl_b64 s[46:47], s[46:47], 5
	s_add_u32 s46, s50, s46
	s_addc_u32 s47, s51, s47
	v_add_f32_e32 v12, v12, v13
	global_store_dword v209, v12, s[46:47]

.LBB0_623:
	s_and_b64 vcc, exec, s[12:13]
	s_cbranch_vccnz .LBB0_627
	v_mul_f32_e32 v9, v9, v9
	v_fmac_f32_e32 v9, v8, v8
	v_mul_f32_e32 v8, v11, v11
	v_fmac_f32_e32 v8, v10, v10
	v_add_f32_e32 v8, v9, v8
	s_nop 1
	v_add_f32_dpp v8, v8, v8 quad_perm:[1,0,3,2] row_mask:0xf bank_mask:0xf
	s_nop 1
	v_add_f32_dpp v8, v8, v8 quad_perm:[2,3,0,1] row_mask:0xf bank_mask:0xf
	s_nop 1
	v_add_f32_dpp v8, v8, v8 row_half_mirror row_mask:0xf bank_mask:0xf
	s_nop 1
	v_add_f32_dpp v8, v8, v8 row_mirror row_mask:0xf bank_mask:0xf
	v_mov_b32_e32 v9, v8
	s_nop 1
	v_permlane16_swap_b32_e32 v8, v9
	v_add_f32_e32 v8, v8, v9
	v_mov_b32_e32 v9, v8
	s_nop 1
	v_permlane32_swap_b32_e32 v8, v9
	s_and_saveexec_b64 s[42:43], s[4:5]
	s_cbranch_execz .LBB0_626
	s_add_i32 s46, s28, s37
	s_ashr_i32 s47, s46, 31
	s_lshl_b64 s[46:47], s[46:47], 5
	s_add_u32 s46, s50, s46
	s_addc_u32 s47, s51, s47
	v_add_f32_e32 v8, v8, v9
	global_store_dword v209, v8, s[46:47]

.LBB0_631:
	s_and_b64 vcc, exec, s[12:13]
	s_cbranch_vccnz .LBB0_635
	v_mul_f32_e32 v5, v5, v5
	v_fmac_f32_e32 v5, v4, v4
	v_mul_f32_e32 v4, v7, v7
	v_fmac_f32_e32 v4, v6, v6
	v_add_f32_e32 v4, v5, v4
	s_nop 1
	v_add_f32_dpp v4, v4, v4 quad_perm:[1,0,3,2] row_mask:0xf bank_mask:0xf
	s_nop 1
	v_add_f32_dpp v4, v4, v4 quad_perm:[2,3,0,1] row_mask:0xf bank_mask:0xf
	s_nop 1
	v_add_f32_dpp v4, v4, v4 row_half_mirror row_mask:0xf bank_mask:0xf
	s_nop 1
	v_add_f32_dpp v4, v4, v4 row_mirror row_mask:0xf bank_mask:0xf
	v_mov_b32_e32 v5, v4
	s_nop 1
	v_permlane16_swap_b32_e32 v4, v5
	v_add_f32_e32 v4, v4, v5
	v_mov_b32_e32 v5, v4
	s_nop 1
	v_permlane32_swap_b32_e32 v4, v5
	s_and_saveexec_b64 s[42:43], s[4:5]
	s_cbranch_execz .LBB0_634
	s_add_i32 s46, s28, s48
	s_ashr_i32 s47, s46, 31
	s_lshl_b64 s[46:47], s[46:47], 5
	s_add_u32 s46, s50, s46
	s_addc_u32 s47, s51, s47
	v_add_f32_e32 v4, v4, v5
	global_store_dword v209, v4, s[46:47]

.LBB0_639:
	s_and_b64 vcc, exec, s[12:13]
	s_cbranch_vccnz .LBB0_527
	v_mul_f32_e32 v1, v1, v1
	v_fmac_f32_e32 v1, v0, v0
	v_mul_f32_e32 v0, v3, v3
	v_fmac_f32_e32 v0, v2, v2
	v_add_f32_e32 v0, v1, v0
	s_nop 1
	v_add_f32_dpp v0, v0, v0 quad_perm:[1,0,3,2] row_mask:0xf bank_mask:0xf
	s_nop 1
	v_add_f32_dpp v0, v0, v0 quad_perm:[2,3,0,1] row_mask:0xf bank_mask:0xf
	s_nop 1
	v_add_f32_dpp v0, v0, v0 row_half_mirror row_mask:0xf bank_mask:0xf
	s_nop 1
	v_add_f32_dpp v0, v0, v0 row_mirror row_mask:0xf bank_mask:0xf
	v_mov_b32_e32 v1, v0
	s_nop 1
	v_permlane16_swap_b32_e32 v0, v1
	v_add_f32_e32 v0, v0, v1
	v_mov_b32_e32 v1, v0
	s_nop 1
	v_permlane32_swap_b32_e32 v0, v1
	s_and_saveexec_b64 s[10:11], s[4:5]
	s_cbranch_execz .LBB0_526
	s_add_i32 s12, s28, s49
	s_ashr_i32 s13, s12, 31
	s_lshl_b64 s[12:13], s[12:13], 5
	s_add_u32 s12, s50, s12
	s_addc_u32 s13, s51, s13
	v_add_f32_e32 v0, v0, v1
	global_store_dword v209, v0, s[12:13]
	s_branch .LBB0_526

.LBB0_921:
	v_lshl_add_u64 v[136:137], v[132:133], 0, s[2:3]
	v_add_co_u32_e32 v152, vcc, 0xa800000, v136
	v_mfma_f32_32x32x16_bf16 v[32:47], v[48:51], v[64:67], 0
	s_nop 0
	v_addc_co_u32_e32 v153, vcc, 0, v137, vcc
	global_load_dwordx2 v[140:141], v[152:153], off
	global_load_dwordx2 v[138:139], v[152:153], off offset:16
	s_mov_b32 s4, 0xc800000
	s_add_u32 s2, s2, 0x20000
	s_addc_u32 s3, s3, 0
	s_cmp_lg_u32 s2, 0x200000
	v_mfma_f32_32x32x16_bf16 v[16:31], v[48:51], v[68:71], 0
	v_mfma_f32_32x32x16_bf16 v[0:15], v[48:51], v[72:75], 0
	v_mfma_f32_32x32x16_bf16 v[48:63], v[48:51], v[76:79], 0
	s_nop 9
	v_permlane32_swap_b32_e32 v32, v16
	v_permlane32_swap_b32_e32 v33, v17
	v_permlane32_swap_b32_e32 v34, v18
	v_permlane32_swap_b32_e32 v35, v19
	v_permlane32_swap_b32_e32 v36, v20
	v_permlane32_swap_b32_e32 v37, v21
	v_permlane32_swap_b32_e32 v38, v22
	v_permlane32_swap_b32_e32 v39, v23
	v_permlane32_swap_b32_e32 v40, v24
	v_permlane32_swap_b32_e32 v41, v25
	v_permlane32_swap_b32_e32 v42, v26
	v_permlane32_swap_b32_e32 v43, v27
	v_permlane32_swap_b32_e32 v44, v28
	v_permlane32_swap_b32_e32 v45, v29
	v_permlane32_swap_b32_e32 v46, v30
	v_permlane32_swap_b32_e32 v47, v31
	v_permlane32_swap_b32_e32 v0, v48
	v_permlane32_swap_b32_e32 v1, v49
	v_permlane32_swap_b32_e32 v2, v50
	v_permlane32_swap_b32_e32 v3, v51
	v_permlane32_swap_b32_e32 v4, v52
	v_permlane32_swap_b32_e32 v5, v53
	v_permlane32_swap_b32_e32 v6, v54
	v_permlane32_swap_b32_e32 v7, v55
	v_permlane32_swap_b32_e32 v8, v56
	v_permlane32_swap_b32_e32 v9, v57
	v_permlane32_swap_b32_e32 v10, v58
	v_permlane32_swap_b32_e32 v11, v59
	v_permlane32_swap_b32_e32 v12, v60
	v_permlane32_swap_b32_e32 v13, v61
	v_permlane32_swap_b32_e32 v14, v62
	v_permlane32_swap_b32_e32 v15, v63
	v_fma_f32 v32, -v125, v142, v32
	v_fma_f32 v0, v125, v143, v0
	v_fmac_f32_e32 v32, v124, v143
	v_fmac_f32_e32 v0, v124, v142
	v_cvt_pk_bf16_f32 v154, v32, v0
	ds_write_b32 v150, v154 offset:8192
	v_fma_f32 v33, -v125, v0, v33
	v_fma_f32 v1, v125, v32, v1
	v_fmac_f32_e32 v33, v124, v32
	v_fmac_f32_e32 v1, v124, v0
	v_cvt_pk_bf16_f32 v154, v33, v1
	ds_write_b32 v150, v154 offset:8464
	v_fma_f32 v34, -v125, v1, v34
	v_fma_f32 v2, v125, v33, v2
	v_fmac_f32_e32 v34, v124, v33
	v_fmac_f32_e32 v2, v124, v1
	v_cvt_pk_bf16_f32 v154, v34, v2
	ds_write_b32 v150, v154 offset:8736
	v_fma_f32 v35, -v125, v2, v35
	v_fma_f32 v3, v125, v34, v3
	v_fmac_f32_e32 v35, v124, v34
	v_fmac_f32_e32 v3, v124, v2
	v_cvt_pk_bf16_f32 v154, v35, v3
	ds_write_b32 v150, v154 offset:9008
	v_fma_f32 v16, -v125, v3, v16
	v_fma_f32 v48, v125, v35, v48
	v_fmac_f32_e32 v16, v124, v35
	v_fmac_f32_e32 v48, v124, v3
	v_cvt_pk_bf16_f32 v154, v16, v48
	ds_write_b32 v150, v154 offset:9280
	v_fma_f32 v17, -v125, v48, v17
	v_fma_f32 v49, v125, v16, v49
	v_fmac_f32_e32 v17, v124, v16
	v_fmac_f32_e32 v49, v124, v48
	v_cvt_pk_bf16_f32 v154, v17, v49
	ds_write_b32 v150, v154 offset:9552
	v_fma_f32 v18, -v125, v49, v18
	v_fma_f32 v50, v125, v17, v50
	v_fmac_f32_e32 v18, v124, v17
	v_fmac_f32_e32 v50, v124, v49
	v_cvt_pk_bf16_f32 v154, v18, v50
	ds_write_b32 v150, v154 offset:9824
	v_fma_f32 v19, -v125, v50, v19
	v_fma_f32 v51, v125, v18, v51
	v_fmac_f32_e32 v19, v124, v18
	v_fmac_f32_e32 v51, v124, v50
	v_cvt_pk_bf16_f32 v154, v19, v51
	ds_write_b32 v150, v154 offset:10096
	v_fma_f32 v36, -v125, v51, v36
	v_fma_f32 v4, v125, v19, v4
	v_fmac_f32_e32 v36, v124, v19
	v_fmac_f32_e32 v4, v124, v51
	v_cvt_pk_bf16_f32 v154, v36, v4
	ds_write_b32 v150, v154 offset:10368
	v_fma_f32 v37, -v125, v4, v37
	v_fma_f32 v5, v125, v36, v5
	v_fmac_f32_e32 v37, v124, v36
	v_fmac_f32_e32 v5, v124, v4
	v_cvt_pk_bf16_f32 v154, v37, v5
	ds_write_b32 v150, v154 offset:10640
	v_fma_f32 v38, -v125, v5, v38
	v_fma_f32 v6, v125, v37, v6
	v_fmac_f32_e32 v38, v124, v37
	v_fmac_f32_e32 v6, v124, v5
	v_cvt_pk_bf16_f32 v154, v38, v6
	ds_write_b32 v150, v154 offset:10912
	v_fma_f32 v39, -v125, v6, v39
	v_fma_f32 v7, v125, v38, v7
	v_fmac_f32_e32 v39, v124, v38
	v_fmac_f32_e32 v7, v124, v6
	v_cvt_pk_bf16_f32 v154, v39, v7
	ds_write_b32 v150, v154 offset:11184
	v_fma_f32 v20, -v125, v7, v20
	v_fma_f32 v52, v125, v39, v52
	v_fmac_f32_e32 v20, v124, v39
	v_fmac_f32_e32 v52, v124, v7
	v_cvt_pk_bf16_f32 v154, v20, v52
	ds_write_b32 v150, v154 offset:11456
	v_fma_f32 v21, -v125, v52, v21
	v_fma_f32 v53, v125, v20, v53
	v_fmac_f32_e32 v21, v124, v20
	v_fmac_f32_e32 v53, v124, v52
	v_cvt_pk_bf16_f32 v154, v21, v53
	ds_write_b32 v150, v154 offset:11728
	v_fma_f32 v22, -v125, v53, v22
	v_fma_f32 v54, v125, v21, v54
	v_fmac_f32_e32 v22, v124, v21
	v_fmac_f32_e32 v54, v124, v53
	v_cvt_pk_bf16_f32 v154, v22, v54
	ds_write_b32 v150, v154 offset:12000
	v_fma_f32 v23, -v125, v54, v23
	v_fma_f32 v55, v125, v22, v55
	v_fmac_f32_e32 v23, v124, v22
	v_fmac_f32_e32 v55, v124, v54
	v_cvt_pk_bf16_f32 v154, v23, v55
	ds_write_b32 v150, v154 offset:12272
	v_fma_f32 v40, -v125, v55, v40
	v_fma_f32 v8, v125, v23, v8
	v_fmac_f32_e32 v40, v124, v23
	v_fmac_f32_e32 v8, v124, v55
	v_cvt_pk_bf16_f32 v154, v40, v8
	ds_write_b32 v150, v154 offset:12544
	v_fma_f32 v41, -v125, v8, v41
	v_fma_f32 v9, v125, v40, v9
	v_fmac_f32_e32 v41, v124, v40
	v_fmac_f32_e32 v9, v124, v8
	v_cvt_pk_bf16_f32 v154, v41, v9
	ds_write_b32 v150, v154 offset:12816
	v_fma_f32 v42, -v125, v9, v42
	v_fma_f32 v10, v125, v41, v10
	v_fmac_f32_e32 v42, v124, v41
	v_fmac_f32_e32 v10, v124, v9
	v_cvt_pk_bf16_f32 v154, v42, v10
	ds_write_b32 v150, v154 offset:13088
	v_fma_f32 v43, -v125, v10, v43
	v_fma_f32 v11, v125, v42, v11
	v_fmac_f32_e32 v43, v124, v42
	v_fmac_f32_e32 v11, v124, v10
	v_cvt_pk_bf16_f32 v154, v43, v11
	ds_write_b32 v150, v154 offset:13360
	v_fma_f32 v24, -v125, v11, v24
	v_fma_f32 v56, v125, v43, v56
	v_fmac_f32_e32 v24, v124, v43
	v_fmac_f32_e32 v56, v124, v11
	v_cvt_pk_bf16_f32 v154, v24, v56
	ds_write_b32 v150, v154 offset:13632
	v_fma_f32 v25, -v125, v56, v25
	v_fma_f32 v57, v125, v24, v57
	v_fmac_f32_e32 v25, v124, v24
	v_fmac_f32_e32 v57, v124, v56
	v_cvt_pk_bf16_f32 v154, v25, v57
	ds_write_b32 v150, v154 offset:13904
	v_fma_f32 v26, -v125, v57, v26
	v_fma_f32 v58, v125, v25, v58
	v_fmac_f32_e32 v26, v124, v25
	v_fmac_f32_e32 v58, v124, v57
	v_cvt_pk_bf16_f32 v154, v26, v58
	ds_write_b32 v150, v154 offset:14176
	v_fma_f32 v27, -v125, v58, v27
	v_fma_f32 v59, v125, v26, v59
	v_fmac_f32_e32 v27, v124, v26
	v_fmac_f32_e32 v59, v124, v58
	v_cvt_pk_bf16_f32 v154, v27, v59
	ds_write_b32 v150, v154 offset:14448
	v_fma_f32 v44, -v125, v59, v44
	v_fma_f32 v12, v125, v27, v12
	v_fmac_f32_e32 v44, v124, v27
	v_fmac_f32_e32 v12, v124, v59
	v_cvt_pk_bf16_f32 v154, v44, v12
	ds_write_b32 v150, v154 offset:14720
	v_fma_f32 v45, -v125, v12, v45
	v_fma_f32 v13, v125, v44, v13
	v_fmac_f32_e32 v45, v124, v44
	v_fmac_f32_e32 v13, v124, v12
	v_cvt_pk_bf16_f32 v154, v45, v13
	ds_write_b32 v150, v154 offset:14992
	v_fma_f32 v46, -v125, v13, v46
	v_fma_f32 v14, v125, v45, v14
	v_fmac_f32_e32 v46, v124, v45
	v_fmac_f32_e32 v14, v124, v13
	v_cvt_pk_bf16_f32 v154, v46, v14
	ds_write_b32 v150, v154 offset:15264
	v_fma_f32 v47, -v125, v14, v47
	v_fma_f32 v15, v125, v46, v15
	v_fmac_f32_e32 v47, v124, v46
	v_fmac_f32_e32 v15, v124, v14
	v_cvt_pk_bf16_f32 v154, v47, v15
	ds_write_b32 v150, v154 offset:15536
	v_fma_f32 v28, -v125, v15, v28
	v_fma_f32 v60, v125, v47, v60
	v_fmac_f32_e32 v28, v124, v47
	v_fmac_f32_e32 v60, v124, v15
	v_cvt_pk_bf16_f32 v154, v28, v60
	ds_write_b32 v150, v154 offset:15808
	v_fma_f32 v29, -v125, v60, v29
	v_fma_f32 v61, v125, v28, v61
	v_fmac_f32_e32 v29, v124, v28
	v_fmac_f32_e32 v61, v124, v60
	v_cvt_pk_bf16_f32 v154, v29, v61
	ds_write_b32 v150, v154 offset:16080
	v_fma_f32 v30, -v125, v61, v30
	v_fma_f32 v62, v125, v29, v62
	v_fmac_f32_e32 v30, v124, v29
	v_fmac_f32_e32 v62, v124, v61
	v_cvt_pk_bf16_f32 v154, v30, v62
	ds_write_b32 v150, v154 offset:16352
	v_fma_f32 v143, -v125, v62, v31
	v_fma_f32 v142, v125, v30, v63
	v_fmac_f32_e32 v143, v124, v30
	v_fmac_f32_e32 v142, v124, v62
	v_cvt_pk_bf16_f32 v154, v143, v142
	ds_write_b32 v150, v154 offset:16624
	ds_read_b128 v[0:3], v151 offset:8192
	ds_read_b128 v[16:19], v151 offset:8224
	s_waitcnt lgkmcnt(1)
	v_mfma_f32_32x32x16_bf16 v[0:15], v[84:87], v[0:3], 0
	s_waitcnt lgkmcnt(0)
	v_mfma_f32_32x32x16_bf16 v[0:15], v[80:83], v[16:19], v[0:15]
	ds_read_b128 v[16:19], v151 offset:8256
	ds_read_b128 v[20:23], v151 offset:8288
	s_waitcnt lgkmcnt(1)
	v_mfma_f32_32x32x16_bf16 v[0:15], v[88:91], v[16:19], v[0:15]
	s_waitcnt lgkmcnt(0)
	v_mfma_f32_32x32x16_bf16 v[0:15], v[92:95], v[20:23], v[0:15]
	ds_read_b128 v[16:19], v151 offset:8320
	ds_read_b128 v[20:23], v151 offset:8352
	s_waitcnt lgkmcnt(1)
	v_mfma_f32_32x32x16_bf16 v[0:15], v[96:99], v[16:19], v[0:15]
	s_waitcnt lgkmcnt(0)
	v_mfma_f32_32x32x16_bf16 v[0:15], v[100:103], v[20:23], v[0:15]
	ds_read_b128 v[16:19], v151 offset:8384
	ds_read_b128 v[20:23], v151 offset:8416
	s_waitcnt lgkmcnt(1)
	v_mfma_f32_32x32x16_bf16 v[0:15], v[104:107], v[16:19], v[0:15]
	s_waitcnt lgkmcnt(0)
	v_mfma_f32_32x32x16_bf16 v[0:15], v[108:111], v[20:23], v[0:15]
	s_waitcnt vmcnt(1)
	s_nop 10
	v_and_b32_e32 v9, 0xffff0000, v140
	v_lshlrev_b32_e32 v10, 16, v141
	v_fma_f32 v1, v113, v9, v1
	v_fma_f32 v2, v114, v10, v2
	v_mul_f32_e32 v9, v1, v1
	v_mul_f32_e32 v10, v2, v2
	v_fmamk_f32 v9, v9, 0xbdd2d3e8, v246
	v_fmamk_f32 v10, v10, 0xbdd2d3e8, v246
	v_lshlrev_b32_e32 v8, 16, v140
	v_mul_f32_e32 v9, v1, v9
	v_mul_f32_e32 v10, v2, v10
	v_fma_f32 v0, v112, v8, v0
	v_exp_f32_e32 v9, v9
	v_exp_f32_e32 v10, v10
	v_mul_f32_e32 v8, v0, v0
	v_fmamk_f32 v8, v8, 0xbdd2d3e8, v246
	v_mul_f32_e32 v8, v0, v8
	v_exp_f32_e32 v8, v8
	v_add_f32_e32 v9, 1.0, v9
	v_add_f32_e32 v10, 1.0, v10
	v_and_b32_e32 v11, 0xffff0000, v141
	v_rcp_f32_e32 v9, v9
	v_rcp_f32_e32 v10, v10
	v_fma_f32 v3, v115, v11, v3
	v_mul_f32_e32 v11, v3, v3
	v_fmamk_f32 v11, v11, 0xbdd2d3e8, v246
	v_add_f32_e32 v8, 1.0, v8
	v_mul_f32_e32 v11, v3, v11
	v_rcp_f32_e32 v8, v8
	v_exp_f32_e32 v11, v11
	v_mul_f32_e32 v1, v1, v9
	v_mul_f32_e32 v2, v2, v10
	s_waitcnt vmcnt(0)
	v_lshlrev_b32_e32 v9, 16, v138
	v_and_b32_e32 v10, 0xffff0000, v138
	v_fma_f32 v4, v116, v9, v4
	v_fma_f32 v5, v117, v10, v5
	v_mul_f32_e32 v9, v4, v4
	v_mul_f32_e32 v10, v5, v5
	v_fmamk_f32 v9, v9, 0xbdd2d3e8, v246
	v_fmamk_f32 v10, v10, 0xbdd2d3e8, v246
	v_mul_f32_e32 v0, v0, v8
	v_add_f32_e32 v8, 1.0, v11
	v_mul_f32_e32 v9, v4, v9
	v_mul_f32_e32 v10, v5, v10
	v_rcp_f32_e32 v8, v8
	v_exp_f32_e32 v9, v9
	v_exp_f32_e32 v10, v10
	v_and_b32_e32 v11, 0xffff0000, v139
	v_mul_f32_e32 v3, v3, v8
	v_add_f32_e32 v8, 1.0, v9
	v_add_f32_e32 v9, 1.0, v10
	v_lshlrev_b32_e32 v10, 16, v139
	v_fma_f32 v6, v118, v10, v6
	v_fmac_f32_e32 v7, v119, v11
	v_mul_f32_e32 v10, v6, v6
	v_mul_f32_e32 v11, v7, v7
	v_fmamk_f32 v10, v10, 0xbdd2d3e8, v246
	v_fmamk_f32 v11, v11, 0xbdd2d3e8, v246
	v_mul_f32_e32 v10, v6, v10
	v_mul_f32_e32 v11, v7, v11
	v_exp_f32_e32 v10, v10
	v_exp_f32_e32 v11, v11
	v_rcp_f32_e32 v8, v8
	v_rcp_f32_e32 v9, v9
	v_add_f32_e32 v10, 1.0, v10
	v_add_f32_e32 v11, 1.0, v11
	v_rcp_f32_e32 v10, v10
	v_rcp_f32_e32 v11, v11
	v_cvt_pk_bf16_f32 v0, v0, v1
	v_cvt_pk_bf16_f32 v1, v2, v3
	v_add_co_u32_e32 v2, vcc, s4, v136
	v_mul_f32_e32 v4, v4, v8
	s_nop 0
	v_addc_co_u32_e32 v3, vcc, 0, v137, vcc
	v_mul_f32_e32 v5, v5, v9
	v_mul_f32_e32 v6, v6, v10
	v_mul_f32_e32 v7, v7, v11
	global_store_dwordx2 v[2:3], v[0:1], off
	v_cvt_pk_bf16_f32 v0, v4, v5
	v_cvt_pk_bf16_f32 v1, v6, v7
	global_store_dwordx2 v[2:3], v[0:1], off offset:16
	v_mov_b64_e32 v[48:49], v[120:121]
	v_mov_b64_e32 v[50:51], v[122:123]
	s_cbranch_scc0 .LBB0_924
